# static s_setprio 1 for waves 4-7 during the attention phase to de-phase the two waves sharing a SIMD
# speedup vs baseline: 1.0033x; 1.0033x over previous
; __device__ __forceinline__ void dsa_attend(const h16* PROJ, const unsigned short* IDX, const int* CNT, h16* MIXA, unsigned char* shm, unsigned* bar, unsigned xcc, unsigned xrank) {
;     ...
;     for (int u = 0; u < 2 * NBATCH; ++u) {
;         int rank, total; if (!xcd_unit_rank(bar, xcc, xrank, 2 * NBATCH, u, rank, total)) continue;
;         const int b = u >> 1, g = u & 1, tokbase = b * SEQ;
;         for (int it = rank; it < 1024; it += total) {
;             const int t = it * 8 + wid, tokq = tokbase + t; int nsel = __builtin_amdgcn_readfirstlane(CNT[tokq]); nsel = nsel < 1 ? 1 : (nsel > 256 ? 256 : nsel);
.LBB0_841:
	s_movk_i32 s60, 0x400
	v_cmp_gt_i32_e32 vcc, s60, v220
	s_and_b64 s[50:51], s[50:51], vcc
	s_andn2_b64 vcc, exec, s[50:51]
	s_cbranch_vccnz .LBB0_808
	s_lshl_b32 s50, s83, 12
	s_and_b32 s50, s50, 0x6000
	v_add_u32_e32 v221, s50, v188
	s_lshl_b32 s50, s83, 9
	s_and_b32 s50, s50, 0x200
	s_lshl_b32 s70, s83, 20
	v_add_lshl_u32 v162, s50, v192, 1
	v_lshl_add_u64 v[140:141], v[132:133], 0, s[70:71]
	v_cmp_lt_u32_e32 vcc, 0xff, v160
	s_cbranch_vccz .Lmy_att_noprio
	s_setprio 1
.Lmy_att_noprio:
	s_nop 1
	v_readfirstlane_b32 s98, v140
	v_readfirstlane_b32 s99, v141
	v_lshl_add_u32 v240, v189, 1, v190
	v_lshl_add_u32 v241, v193, 1, v190
	v_and_b32_e32 v242, 48, v216
	v_lshlrev_b32_e32 v243, 4, v216
	v_and_b32_e32 v243, 0x70, v243
	v_add_u32_e32 v243, 0x1000000, v243
	v_mov_b32_e32 v244, 0x3e0293ee
	v_lshl_add_u64 v[142:143], v[134:135], 0, s[70:71]
	s_lshl_b32 s70, s50, 1
	v_lshl_add_u64 v[138:139], v[130:131], 0, v[162:163]
	v_lshl_add_u64 v[144:145], v[136:137], 0, s[70:71]
	v_mov_b32_e32 v222, v220
	s_branch .LBB0_844

; __global__ void __launch_bounds__(512, 2) fwd_megakernel(Params P) {
;     ...
;             case K_CARRY:
;                 dsa_attend(R1, (const unsigned short*)(ws + OFF_R1 + R1_IDX), (const int*)(ws + OFF_R1 + R1_CNT), MIXA, shm, (unsigned*)(ws + OFF_BAR), xbst[3], xbst[2]);
;                 break;
;     ...
;             xcd_barrier((unsigned*)(ws + OFF_BAR), xbst);
.LBB0_853:
	s_setprio 0
	v_readlane_b32 s84, v254, 46
	v_readlane_b32 s86, v254, 48
	v_readlane_b32 s64, v254, 50
	v_readlane_b32 s88, v254, 53
	v_readlane_b32 s92, v254, 56
	v_readlane_b32 s94, v254, 58
	v_readlane_b32 s56, v255, 1
	v_readlane_b32 s58, v255, 3
	v_readlane_b32 s48, v255, 38
	v_readlane_b32 s60, v255, 42
	v_readlane_b32 s62, v255, 40
	s_mov_b64 s[0:1], 0
	v_readlane_b32 s85, v254, 47
	v_readlane_b32 s87, v254, 49
	v_readlane_b32 s65, v254, 51
	v_readlane_b32 s67, v254, 52
	v_readlane_b32 s89, v254, 54
	v_readlane_b32 s69, v254, 55
	v_readlane_b32 s93, v254, 57
	v_readlane_b32 s95, v254, 59
	v_readlane_b32 s96, v254, 60
	v_readlane_b32 s68, v254, 61
	v_readlane_b32 s83, v254, 62
	s_movk_i32 s51, 0xc00
	s_mov_b32 s52, 0xf800000
	v_readlane_b32 s53, v254, 63
	v_readlane_b32 s54, v255, 0
	v_readlane_b32 s57, v255, 2
	v_readlane_b32 s59, v255, 4
	v_readlane_b32 s55, v255, 29
	v_readlane_b32 s47, v255, 37
	v_readlane_b32 s49, v255, 39
	v_readlane_b32 s61, v255, 43
	v_readlane_b32 s63, v255, 41
